# grid barrier: non-leader workgroups poll the cross-XCD generation word directly instead of the per-XCD one (one hop less on the release path)
# speedup vs baseline: 1.0072x; 1.0072x over previous
; __device__ __forceinline__ unsigned xb_ld(unsigned* p)              { return __hip_atomic_load(p, __ATOMIC_RELAXED, __HIP_MEMORY_SCOPE_AGENT); }
; __device__ __forceinline__ unsigned xb_add(unsigned* p, unsigned v) { return __hip_atomic_fetch_add(p, v, __ATOMIC_RELAXED, __HIP_MEMORY_SCOPE_AGENT); }
; #define XB_SPIN(cond, bar) do { unsigned _sp = 0; while (cond) { __builtin_amdgcn_s_sleep(1); \
;     if ((++_sp & 255u) == 0u) { if (xb_ld(&(bar)[XB_TMO])) break; if (_sp > XB_SPIN_CAP) { atomicAdd(&(bar)[XB_TMO], 1u); break; } } } } while (0)
; __device__ __forceinline__ void xcd_barrier(const XcdBarrier& b, int xtid) {
;     asm volatile("s_waitcnt vmcnt(0)" ::: "memory");
;     __syncthreads();
;     if (xtid == 0) {
;         unsigned* bar = b.bar; unsigned bx_ = b.x; asm volatile("" : "+s"(bx_));
;         __builtin_amdgcn_s_waitcnt(0);
;         unsigned nloc = b.st[0], nx = b.st[1];
;         if (nloc == 0u) { xcd_barrier_complete(bar, bx_, nloc, nx); b.st[0] = nloc; b.st[1] = nx; }
;         const unsigned old = xb_add(&bar[XB_XSUB(bx_)], 1u);
;         const unsigned gen = old / nloc;
;         if (old + 1u == (gen + 1u) * nloc) {
;             __builtin_amdgcn_fence(__ATOMIC_RELEASE, "agent");
;             asm volatile("s_waitcnt vmcnt(0)" ::: "memory");
;             const unsigned og = xb_add(&bar[XB_TOP], 1u);
;             const unsigned tg = og / nx;
;             if (og + 1u == (tg + 1u) * nx) xb_add(&bar[XB_TOPGEN], 1u);
;             else XB_SPIN(xb_ld(&bar[XB_TOPGEN]) == tg, bar);
;             __builtin_amdgcn_fence(__ATOMIC_ACQUIRE, "agent");
;             xb_add(&bar[XB_XGEN(bx_)], 1u);
;             asm volatile("s_waitcnt vmcnt(0)" ::: "memory");
;         } else {
;             XB_SPIN(xb_ld(&bar[XB_XGEN(bx_)]) == gen, bar);
.LBB0_79:
	s_or_b64 exec, exec, s[8:9]
	v_cvt_f32_u32_e32 v4, v2
	s_waitcnt vmcnt(0)
	v_readfirstlane_b32 s6, v3
	v_sub_u32_e32 v3, 0, v2
	v_rcp_iflag_f32_e32 v4, v4
	v_add_u32_e32 v5, s6, v1
	v_mul_f32_e32 v4, 0x4f7ffffe, v4
	v_cvt_u32_f32_e32 v4, v4
	v_mul_lo_u32 v1, v3, v4
	v_mul_hi_u32 v1, v4, v1
	v_add_u32_e32 v1, v4, v1
	v_mul_hi_u32 v1, v5, v1
	v_mul_lo_u32 v3, v1, v2
	v_sub_u32_e32 v3, v5, v3
	v_add_u32_e32 v4, 1, v1
	v_cmp_ge_u32_e32 vcc, v3, v2
	s_nop 1
	v_cndmask_b32_e32 v1, v1, v4, vcc
	v_sub_u32_e32 v4, v3, v2
	v_cndmask_b32_e32 v3, v3, v4, vcc
	v_add_u32_e32 v4, 1, v1
	v_cmp_ge_u32_e32 vcc, v3, v2
	v_add_u32_e32 v3, 1, v5
	s_nop 0
	v_cndmask_b32_e32 v1, v1, v4, vcc
	v_mul_lo_u32 v4, v2, v1
	v_add_u32_e32 v2, v4, v2
	v_cmp_ne_u32_e32 vcc, v3, v2
	s_and_saveexec_b64 s[6:7], vcc
	s_xor_b64 s[6:7], exec, s[6:7]
	s_cbranch_execz .LBB0_93
	s_mov_b32 s96, 0xd40
	s_lshl_b64 s[8:9], s[96:97], 2
	s_add_u32 s10, s66, s8
	s_addc_u32 s11, s67, s9
	s_waitcnt lgkmcnt(0)
	global_load_dword v0, v161, s[10:11] sc1
	s_waitcnt vmcnt(0)
	v_cmp_eq_u32_e32 vcc, v0, v1
	s_and_saveexec_b64 s[8:9], vcc
	s_cbranch_execz .LBB0_92
	s_mov_b32 s22, 1
	s_mov_b64 s[12:13], 0
	s_branch .LBB0_83

; __device__ __forceinline__ unsigned xb_ld(unsigned* p)              { return __hip_atomic_load(p, __ATOMIC_RELAXED, __HIP_MEMORY_SCOPE_AGENT); }
; __device__ __forceinline__ unsigned xb_add(unsigned* p, unsigned v) { return __hip_atomic_fetch_add(p, v, __ATOMIC_RELAXED, __HIP_MEMORY_SCOPE_AGENT); }
; #define XB_SPIN(cond, bar) do { unsigned _sp = 0; while (cond) { __builtin_amdgcn_s_sleep(1); \
;     if ((++_sp & 255u) == 0u) { if (xb_ld(&(bar)[XB_TMO])) break; if (_sp > XB_SPIN_CAP) { atomicAdd(&(bar)[XB_TMO], 1u); break; } } } } while (0)
; __device__ __forceinline__ void xcd_barrier(const XcdBarrier& b, int xtid) {
;     ...
;         const unsigned old = xb_add(&bar[XB_XSUB(bx_)], 1u);
;         const unsigned gen = old / nloc;
;         if (old + 1u == (gen + 1u) * nloc) {
;             __builtin_amdgcn_fence(__ATOMIC_RELEASE, "agent");
;             asm volatile("s_waitcnt vmcnt(0)" ::: "memory");
;             const unsigned og = xb_add(&bar[XB_TOP], 1u);
;             const unsigned tg = og / nx;
;             if (og + 1u == (tg + 1u) * nx) xb_add(&bar[XB_TOPGEN], 1u);
;             else XB_SPIN(xb_ld(&bar[XB_TOPGEN]) == tg, bar);
;             __builtin_amdgcn_fence(__ATOMIC_ACQUIRE, "agent");
;             xb_add(&bar[XB_XGEN(bx_)], 1u);
;             asm volatile("s_waitcnt vmcnt(0)" ::: "memory");
;         } else {
;             XB_SPIN(xb_ld(&bar[XB_XGEN(bx_)]) == gen, bar);
.LBB0_494:
	s_or_b64 exec, exec, s[8:9]
	v_cvt_f32_u32_e32 v4, v2
	s_waitcnt vmcnt(0)
	v_readfirstlane_b32 s6, v3
	v_sub_u32_e32 v3, 0, v2
	v_rcp_iflag_f32_e32 v4, v4
	v_add_u32_e32 v5, s6, v1
	v_mul_f32_e32 v4, 0x4f7ffffe, v4
	v_cvt_u32_f32_e32 v4, v4
	v_mul_lo_u32 v1, v3, v4
	v_mul_hi_u32 v1, v4, v1
	v_add_u32_e32 v1, v4, v1
	v_mul_hi_u32 v1, v5, v1
	v_mul_lo_u32 v3, v1, v2
	v_sub_u32_e32 v3, v5, v3
	v_add_u32_e32 v4, 1, v1
	v_cmp_ge_u32_e32 vcc, v3, v2
	s_nop 1
	v_cndmask_b32_e32 v1, v1, v4, vcc
	v_sub_u32_e32 v4, v3, v2
	v_cndmask_b32_e32 v3, v3, v4, vcc
	v_add_u32_e32 v4, 1, v1
	v_cmp_ge_u32_e32 vcc, v3, v2
	v_add_u32_e32 v3, 1, v5
	s_nop 0
	v_cndmask_b32_e32 v1, v1, v4, vcc
	v_mul_lo_u32 v4, v2, v1
	v_add_u32_e32 v2, v4, v2
	v_cmp_ne_u32_e32 vcc, v3, v2
	s_and_saveexec_b64 s[6:7], vcc
	s_xor_b64 s[6:7], exec, s[6:7]
	s_cbranch_execz .LBB0_508
	s_mov_b32 s96, 0xd40
	s_lshl_b64 s[8:9], s[96:97], 2
	s_add_u32 s10, s66, s8
	s_addc_u32 s11, s67, s9
	s_waitcnt lgkmcnt(0)
	global_load_dword v0, v161, s[10:11] sc1
	s_waitcnt vmcnt(0)
	v_cmp_eq_u32_e32 vcc, v0, v1
	s_and_saveexec_b64 s[8:9], vcc
	s_cbranch_execz .LBB0_507
	s_mov_b32 s13, 1
	s_mov_b64 s[16:17], 0
	s_branch .LBB0_498

; __device__ __forceinline__ unsigned xb_ld(unsigned* p)              { return __hip_atomic_load(p, __ATOMIC_RELAXED, __HIP_MEMORY_SCOPE_AGENT); }
; __device__ __forceinline__ unsigned xb_add(unsigned* p, unsigned v) { return __hip_atomic_fetch_add(p, v, __ATOMIC_RELAXED, __HIP_MEMORY_SCOPE_AGENT); }
; #define XB_SPIN(cond, bar) do { unsigned _sp = 0; while (cond) { __builtin_amdgcn_s_sleep(1); \
;     if ((++_sp & 255u) == 0u) { if (xb_ld(&(bar)[XB_TMO])) break; if (_sp > XB_SPIN_CAP) { atomicAdd(&(bar)[XB_TMO], 1u); break; } } } } while (0)
; __device__ __forceinline__ void xcd_barrier(const XcdBarrier& b, int xtid) {
;     ...
;         const unsigned old = xb_add(&bar[XB_XSUB(bx_)], 1u);
;         const unsigned gen = old / nloc;
;         if (old + 1u == (gen + 1u) * nloc) {
;             __builtin_amdgcn_fence(__ATOMIC_RELEASE, "agent");
;             asm volatile("s_waitcnt vmcnt(0)" ::: "memory");
;             const unsigned og = xb_add(&bar[XB_TOP], 1u);
;             const unsigned tg = og / nx;
;             if (og + 1u == (tg + 1u) * nx) xb_add(&bar[XB_TOPGEN], 1u);
;             else XB_SPIN(xb_ld(&bar[XB_TOPGEN]) == tg, bar);
;             __builtin_amdgcn_fence(__ATOMIC_ACQUIRE, "agent");
;             xb_add(&bar[XB_XGEN(bx_)], 1u);
;             asm volatile("s_waitcnt vmcnt(0)" ::: "memory");
;         } else {
;             XB_SPIN(xb_ld(&bar[XB_XGEN(bx_)]) == gen, bar);
.LBB0_662:
	s_or_b64 exec, exec, s[8:9]
	v_cvt_f32_u32_e32 v4, v2
	s_waitcnt vmcnt(0)
	v_readfirstlane_b32 s6, v3
	v_sub_u32_e32 v3, 0, v2
	v_rcp_iflag_f32_e32 v4, v4
	v_add_u32_e32 v5, s6, v1
	v_mul_f32_e32 v4, 0x4f7ffffe, v4
	v_cvt_u32_f32_e32 v4, v4
	v_mul_lo_u32 v1, v3, v4
	v_mul_hi_u32 v1, v4, v1
	v_add_u32_e32 v1, v4, v1
	v_mul_hi_u32 v1, v5, v1
	v_mul_lo_u32 v3, v1, v2
	v_sub_u32_e32 v3, v5, v3
	v_add_u32_e32 v4, 1, v1
	v_cmp_ge_u32_e32 vcc, v3, v2
	s_nop 1
	v_cndmask_b32_e32 v1, v1, v4, vcc
	v_sub_u32_e32 v4, v3, v2
	v_cndmask_b32_e32 v3, v3, v4, vcc
	v_add_u32_e32 v4, 1, v1
	v_cmp_ge_u32_e32 vcc, v3, v2
	v_add_u32_e32 v3, 1, v5
	s_nop 0
	v_cndmask_b32_e32 v1, v1, v4, vcc
	v_mul_lo_u32 v4, v2, v1
	v_add_u32_e32 v2, v4, v2
	v_cmp_ne_u32_e32 vcc, v3, v2
	s_and_saveexec_b64 s[6:7], vcc
	s_xor_b64 s[6:7], exec, s[6:7]
	s_cbranch_execz .LBB0_676
	s_mov_b32 s96, 0xd40
	s_lshl_b64 s[8:9], s[96:97], 2
	s_add_u32 s10, s66, s8
	s_addc_u32 s11, s67, s9
	s_waitcnt lgkmcnt(0)
	global_load_dword v0, v161, s[10:11] sc1
	s_waitcnt vmcnt(0)
	v_cmp_eq_u32_e32 vcc, v0, v1
	s_and_saveexec_b64 s[8:9], vcc
	s_cbranch_execz .LBB0_675
	s_mov_b32 s13, 1
	s_mov_b64 s[20:21], 0
	s_branch .LBB0_666
